# adds: ml softmax row sums from 8 extra MFMAs per block on wave 0 instead of a 128-long add chain
# speedup vs baseline: 1.0404x; 1.0039x over previous
.LBB0_228:
	s_or_b64 exec, exec, s[0:1]
	s_movk_i32 s0, 0x88
	v_mul_lo_u32 v65, v98, s0
	v_lshlrev_b32_e32 v105, 1, v65
	v_add3_u32 v65, 16, v105, v156
	s_movk_i32 s0, 0x48
	v_lshlrev_b32_e32 v104, 3, v64
	v_lshlrev_b32_e32 v64, 3, v95
	ds_write_b128 v65, v[56:59]
	ds_write_b128 v65, v[60:63] offset:8704
	ds_write_b128 v65, v[0:3] offset:17408
	ds_write_b128 v65, v[4:7] offset:26112
	v_mul_lo_u32 v56, v94, s0
	v_lshlrev_b32_e32 v106, 1, v56
	v_lshlrev_b32_e32 v82, 1, v104
	v_lshl_add_u32 v107, v64, 1, 16
	s_movk_i32 s1, 0x110
	v_add3_u32 v56, 16, v106, v82
	v_mad_u32_u24 v65, v96, s1, v107
	ds_write_b128 v56, v[8:11] offset:34816
	ds_write_b128 v56, v[12:15] offset:44032
	ds_write_b128 v56, v[16:19] offset:53248
	ds_write_b128 v56, v[20:23] offset:62464
	s_waitcnt lgkmcnt(0)
	s_barrier
	ds_read_b128 v[56:59], v65
	ds_read_b128 v[60:63], v65 offset:4352
	ds_read_b128 v[66:69], v65 offset:8704
	ds_read_b128 v[86:89], v65 offset:13056
	s_waitcnt lgkmcnt(3)
	v_mfma_f32_16x16x32_bf16 v[90:93], v[56:59], v[48:51], 0
	s_mov_b32 s19, 0
	v_mov_b32_e32 v83, 0
	s_cmp_lt_i32 s18, 0
	v_mfma_f32_16x16x32_bf16 v[56:59], v[56:59], v[52:55], 0
	v_cmp_gt_i32_e64 s[52:53], 64, v97
	s_waitcnt lgkmcnt(2)
	v_mfma_f32_16x16x32_bf16 v[108:111], v[60:63], v[48:51], 0
	v_mfma_f32_16x16x32_bf16 v[60:63], v[60:63], v[52:55], 0
	s_waitcnt lgkmcnt(1)
	v_mfma_f32_16x16x32_bf16 v[112:115], v[66:69], v[48:51], 0
	v_mfma_f32_16x16x32_bf16 v[66:69], v[66:69], v[52:55], 0
	s_waitcnt lgkmcnt(0)
	v_mfma_f32_16x16x32_bf16 v[48:51], v[86:89], v[48:51], 0
	v_mfma_f32_16x16x32_bf16 v[52:55], v[86:89], v[52:55], 0
	ds_read_b128 v[86:89], v65 offset:64
	ds_read_b128 v[116:119], v65 offset:4416
	ds_read_b128 v[120:123], v65 offset:8768
	ds_read_b128 v[124:127], v65 offset:13120
	s_waitcnt lgkmcnt(3)
	v_mfma_f32_16x16x32_bf16 v[90:93], v[86:89], v[40:43], v[90:93]
	v_mfma_f32_16x16x32_bf16 v[56:59], v[86:89], v[44:47], v[56:59]
	s_waitcnt lgkmcnt(2)
	v_mfma_f32_16x16x32_bf16 v[86:89], v[116:119], v[40:43], v[108:111]
	v_mfma_f32_16x16x32_bf16 v[60:63], v[116:119], v[44:47], v[60:63]
	s_waitcnt lgkmcnt(1)
	v_mfma_f32_16x16x32_bf16 v[108:111], v[120:123], v[40:43], v[112:115]
	v_mfma_f32_16x16x32_bf16 v[66:69], v[120:123], v[44:47], v[66:69]
	s_waitcnt lgkmcnt(0)
	v_mfma_f32_16x16x32_bf16 v[40:43], v[124:127], v[40:43], v[48:51]
	v_mfma_f32_16x16x32_bf16 v[44:47], v[124:127], v[44:47], v[52:55]
	s_nop 1
	ds_read_b128 v[48:51], v65 offset:128
	ds_read_b128 v[52:55], v65 offset:4480
	ds_read_b128 v[112:115], v65 offset:8832
	ds_read_b128 v[116:119], v65 offset:13184
	s_waitcnt lgkmcnt(3)
	v_mfma_f32_16x16x32_bf16 v[90:93], v[48:51], v[32:35], v[90:93]
	v_mfma_f32_16x16x32_bf16 v[48:51], v[48:51], v[36:39], v[56:59]
	s_waitcnt lgkmcnt(2)
	v_mfma_f32_16x16x32_bf16 v[56:59], v[52:55], v[32:35], v[86:89]
	v_mfma_f32_16x16x32_bf16 v[52:55], v[52:55], v[36:39], v[60:63]
	s_waitcnt lgkmcnt(1)
	v_mfma_f32_16x16x32_bf16 v[60:63], v[112:115], v[32:35], v[108:111]
	v_mfma_f32_16x16x32_bf16 v[66:69], v[112:115], v[36:39], v[66:69]
	s_waitcnt lgkmcnt(0)
	v_mfma_f32_16x16x32_bf16 v[86:89], v[116:119], v[32:35], v[40:43]
	v_mfma_f32_16x16x32_bf16 v[108:111], v[116:119], v[36:39], v[44:47]
	ds_read_b128 v[32:35], v65 offset:192
	s_nop 0
	ds_read_b128 v[40:43], v65 offset:4544
	ds_read_b128 v[44:47], v65 offset:8896
	ds_read_b128 v[112:115], v65 offset:13248
	s_waitcnt lgkmcnt(3)
	v_mfma_f32_16x16x32_bf16 v[90:93], v[32:35], v[24:27], v[90:93]
	v_mfma_f32_16x16x32_bf16 v[116:119], v[32:35], v[28:31], v[48:51]
	s_waitcnt lgkmcnt(2)
	v_mfma_f32_16x16x32_bf16 v[36:39], v[40:43], v[24:27], v[56:59]
	v_mfma_f32_16x16x32_bf16 v[48:51], v[40:43], v[28:31], v[52:55]
	s_waitcnt lgkmcnt(1)
	v_mfma_f32_16x16x32_bf16 v[32:35], v[44:47], v[24:27], v[60:63]
	v_mfma_f32_16x16x32_bf16 v[40:43], v[44:47], v[28:31], v[66:69]
	s_waitcnt lgkmcnt(0)
	v_mfma_f32_16x16x32_bf16 v[44:47], v[112:115], v[24:27], v[86:89]
	v_lshl_add_u32 v24, v95, 4, 16
	v_add_u32_e32 v60, 0x23800, v24
	ds_read_b128 v[24:27], v60
	ds_read_b128 v[56:59], v60 offset:64
	v_mfma_f32_16x16x32_bf16 v[52:55], v[112:115], v[28:31], v[108:111]
	s_waitcnt lgkmcnt(1)
	v_sub_f32_e32 v24, v100, v24
	s_waitcnt lgkmcnt(0)
	v_sub_f32_e32 v56, v100, v56
	v_sub_f32_e32 v57, v100, v57
	v_sub_f32_e32 v58, v100, v58
	v_sub_f32_e32 v59, v100, v59
	v_mul_f32_e32 v56, 0x3fb8aa3b, v56
	v_mul_f32_e32 v57, 0x3fb8aa3b, v57
	v_mul_f32_e32 v58, 0x3fb8aa3b, v58
	v_mul_f32_e32 v59, 0x3fb8aa3b, v59
	v_exp_f32_e32 v56, v56
	v_exp_f32_e32 v57, v57
	v_exp_f32_e32 v58, v58
	v_exp_f32_e32 v59, v59
	v_mul_f32_e32 v24, 0x3fb8aa3b, v24
	v_pk_mul_f32 v[36:37], v[36:37], v[56:57]
	v_pk_mul_f32 v[48:49], v[48:49], v[56:57]
	v_pk_mul_f32 v[38:39], v[38:39], v[58:59]
	v_pk_mul_f32 v[50:51], v[50:51], v[58:59]
	ds_read_b128 v[56:59], v60 offset:128
	v_exp_f32_e32 v28, v24
	v_sub_f32_e32 v24, v100, v25
	v_mul_f32_e32 v24, 0x3fb8aa3b, v24
	v_exp_f32_e32 v29, v24
	s_waitcnt lgkmcnt(0)
	v_sub_f32_e32 v56, v100, v56
	v_sub_f32_e32 v57, v100, v57
	v_sub_f32_e32 v58, v100, v58
	v_sub_f32_e32 v59, v100, v59
	v_mul_f32_e32 v56, 0x3fb8aa3b, v56
	v_mul_f32_e32 v57, 0x3fb8aa3b, v57
	v_mul_f32_e32 v58, 0x3fb8aa3b, v58
	v_mul_f32_e32 v59, 0x3fb8aa3b, v59
	v_exp_f32_e32 v56, v56
	v_exp_f32_e32 v57, v57
	v_exp_f32_e32 v58, v58
	v_exp_f32_e32 v59, v59
	v_sub_f32_e32 v24, v100, v26
	v_pk_mul_f32 v[32:33], v[32:33], v[56:57]
	v_pk_mul_f32 v[40:41], v[40:41], v[56:57]
	v_pk_mul_f32 v[34:35], v[34:35], v[58:59]
	v_pk_mul_f32 v[42:43], v[42:43], v[58:59]
	ds_read_b128 v[56:59], v60 offset:192
	v_mul_f32_e32 v24, 0x3fb8aa3b, v24
	v_exp_f32_e32 v30, v24
	v_sub_f32_e32 v24, v100, v27
	v_mul_f32_e32 v24, 0x3fb8aa3b, v24
	s_waitcnt lgkmcnt(0)
	v_sub_f32_e32 v56, v100, v56
	v_sub_f32_e32 v57, v100, v57
	v_sub_f32_e32 v58, v100, v58
	v_sub_f32_e32 v59, v100, v59
	v_mul_f32_e32 v56, 0x3fb8aa3b, v56
	v_mul_f32_e32 v57, 0x3fb8aa3b, v57
	v_mul_f32_e32 v58, 0x3fb8aa3b, v58
	v_mul_f32_e32 v59, 0x3fb8aa3b, v59
	v_exp_f32_e32 v31, v24
	v_exp_f32_e32 v56, v56
	v_exp_f32_e32 v57, v57
	v_exp_f32_e32 v58, v58
	v_exp_f32_e32 v59, v59
	v_pk_mul_f32 v[24:25], v[90:91], v[28:29]
	v_pk_mul_f32 v[26:27], v[92:93], v[30:31]
	v_pk_mul_f32 v[28:29], v[116:117], v[28:29]
	v_pk_mul_f32 v[30:31], v[118:119], v[30:31]
	v_pk_mul_f32 v[44:45], v[44:45], v[56:57]
	v_pk_mul_f32 v[46:47], v[46:47], v[58:59]
	v_pk_mul_f32 v[52:53], v[52:53], v[56:57]
	v_pk_mul_f32 v[54:55], v[54:55], v[58:59]
	s_cbranch_scc1 .LBB0_253
	s_ashr_i32 s0, s12, 3
	s_and_b32 s10, s0, -16
	v_or_b32_e32 v56, s10, v96
	v_mul_lo_u32 v56, v56, s1
	v_lshlrev_b32_e32 v108, 1, v64
	v_add3_u32 v68, 16, v56, v108
	ds_read_b128 v[56:59], v68
	ds_read_b128 v[60:63], v68 offset:64
	ds_read_b128 v[64:67], v68 offset:128
	ds_read_b128 v[68:71], v68 offset:192
	s_add_u32 s0, s62, s28
	s_addc_u32 s1, s63, 0
	v_and_or_b32 v110, s9, 32, v96
	s_lshl_b32 s9, s9, 2
	v_mov_b32_e32 v83, v157
	s_and_b32 s9, s9, 0x80
	v_lshl_add_u64 v[88:89], v[72:73], 0, v[82:83]
	v_lshl_or_b32 v72, v95, 2, s10
	s_add_i32 s9, s9, 16
	v_lshl_add_u64 v[90:91], v[74:75], 0, v[82:83]
	s_movk_i32 s11, 0x90
	v_or_b32_e32 v73, 16, v110
	s_add_i32 s10, 16, 0x23800
	v_or_b32_e32 v74, 1, v72
	v_or_b32_e32 v75, 2, v72
	v_or_b32_e32 v77, 3, v72
	s_add_i32 s9, s9, 0x23400
	v_lshl_add_u64 v[86:87], s[0:1], 0, v[156:157]
	v_lshl_add_u64 v[92:93], v[78:79], 0, v[82:83]
	v_lshl_add_u64 v[84:85], v[84:85], 0, v[82:83]
	v_mul_lo_u32 v109, v97, s11
	v_mul_u32_u24_e32 v111, 0x110, v110
	v_cmp_le_i32_e64 s[0:1], v110, v72
	v_lshl_add_u32 v112, v72, 2, s10
	v_mul_lo_u32 v113, v72, s11
	v_cmp_le_i32_e64 s[38:39], v110, v74
	v_lshl_add_u32 v114, v74, 2, s10
	v_cmp_le_i32_e64 s[40:41], v110, v75
	v_lshl_add_u32 v115, v75, 2, s10
	v_cmp_le_i32_e64 s[42:43], v110, v77
	v_lshl_add_u32 v116, v77, 2, s10
	v_cmp_le_i32_e64 s[44:45], v73, v72
	v_cmp_le_i32_e64 s[46:47], v73, v74
	v_cmp_le_i32_e64 s[48:49], v73, v75
	v_cmp_le_i32_e64 s[50:51], v73, v77
	v_mul_u32_u24_e32 v117, 0x90, v96
	v_mul_lo_u32 v118, v76, s11
	s_add_i32 s8, s8, 64
	s_add_i32 s20, s18, 1
	v_lshl_add_u32 v119, v96, 2, s9
	v_mov_b32_e32 v83, 0
	ds_read_b32 v145, v112
	ds_read_b32 v146, v114
	ds_read_b32 v147, v115
	ds_read_b32 v158, v116
	s_waitcnt lgkmcnt(0)
	v_mov_b32_e32 v220, 0x3f803f80
	v_mov_b32_e32 v221, 0x3f803f80
	v_mov_b32_e32 v222, 0x3f803f80
	v_mov_b32_e32 v223, 0x3f803f80
	v_mov_b32_e32 v136, 0
	v_mov_b32_e32 v137, 0
	v_mov_b32_e32 v138, 0
	v_mov_b32_e32 v139, 0
	v_mov_b32_e32 v140, 0
	v_mov_b32_e32 v141, 0
	v_mov_b32_e32 v142, 0
	v_mov_b32_e32 v143, 0
	v_mov_b32_e32 v148, 0
	v_mov_b32_e32 v149, 0
	v_mov_b32_e32 v150, 0
	v_mov_b32_e32 v151, 0
	v_mov_b32_e32 v152, 0
	v_mov_b32_e32 v153, 0
	v_mov_b32_e32 v154, 0
	v_mov_b32_e32 v155, 0
	s_branch .LBB0_231

.LBB0_251:
	v_add3_u32 v134, s9, v108, v117
	v_add_u32_e32 v135, v120, v118
	ds_read_b128 v[72:75], v134
	ds_read_b128 v[76:79], v134 offset:2304
	ds_read_b128 v[122:125], v134 offset:4608
	ds_read_b128 v[126:129], v134 offset:6912
	ds_read_b128 v[130:133], v135 offset:34816
	s_waitcnt lgkmcnt(0)
	v_mfma_f32_16x16x32_bf16 v[24:27], v[72:75], v[130:133], v[24:27]
	v_mfma_f32_16x16x32_bf16 v[36:39], v[76:79], v[130:133], v[36:39]
	v_mfma_f32_16x16x32_bf16 v[32:35], v[122:125], v[130:133], v[32:35]
	v_mfma_f32_16x16x32_bf16 v[44:47], v[126:129], v[130:133], v[44:47]
	s_cmp_eq_u64 s[52:53], 0
	s_cbranch_scc1 .Lml_nd0
	v_mfma_f32_16x16x32_bf16 v[136:139], v[72:75], v[220:223], v[136:139]
	v_mfma_f32_16x16x32_bf16 v[140:143], v[76:79], v[220:223], v[140:143]
	v_mfma_f32_16x16x32_bf16 v[148:151], v[122:125], v[220:223], v[148:151]
	v_mfma_f32_16x16x32_bf16 v[152:155], v[126:129], v[220:223], v[152:155]
.Lml_nd0:
	ds_read_b128 v[130:133], v135 offset:37120
	s_waitcnt lgkmcnt(0)
	v_mfma_f32_16x16x32_bf16 v[28:31], v[72:75], v[130:133], v[28:31]
	v_mfma_f32_16x16x32_bf16 v[48:51], v[76:79], v[130:133], v[48:51]
	v_mfma_f32_16x16x32_bf16 v[40:43], v[122:125], v[130:133], v[40:43]
	v_mfma_f32_16x16x32_bf16 v[52:55], v[126:129], v[130:133], v[52:55]
	ds_read_b128 v[72:75], v134 offset:64
	ds_read_b128 v[76:79], v134 offset:2368
	ds_read_b128 v[120:123], v134 offset:4672
	ds_read_b128 v[124:127], v134 offset:6976
	ds_read_b128 v[128:131], v135 offset:34880
	s_waitcnt lgkmcnt(0)
	v_mfma_f32_16x16x32_bf16 v[24:27], v[72:75], v[128:131], v[24:27]
	v_mfma_f32_16x16x32_bf16 v[36:39], v[76:79], v[128:131], v[36:39]
	v_mfma_f32_16x16x32_bf16 v[32:35], v[120:123], v[128:131], v[32:35]
	v_mfma_f32_16x16x32_bf16 v[44:47], v[124:127], v[128:131], v[44:47]
	s_cmp_eq_u64 s[52:53], 0
	s_cbranch_scc1 .Lml_nd1
	v_mfma_f32_16x16x32_bf16 v[136:139], v[72:75], v[220:223], v[136:139]
	v_mfma_f32_16x16x32_bf16 v[140:143], v[76:79], v[220:223], v[140:143]
	v_mfma_f32_16x16x32_bf16 v[148:151], v[120:123], v[220:223], v[148:151]
	v_mfma_f32_16x16x32_bf16 v[152:155], v[124:127], v[220:223], v[152:155]
.Lml_nd1:
	ds_read_b128 v[128:131], v135 offset:37184
	s_waitcnt lgkmcnt(0)
	v_mfma_f32_16x16x32_bf16 v[28:31], v[72:75], v[128:131], v[28:31]
	v_mfma_f32_16x16x32_bf16 v[48:51], v[76:79], v[128:131], v[48:51]
	v_mfma_f32_16x16x32_bf16 v[40:43], v[120:123], v[128:131], v[40:43]
	v_mfma_f32_16x16x32_bf16 v[52:55], v[124:127], v[128:131], v[52:55]
	s_mov_b64 s[10:11], exec
	s_branch .LBB0_230
.LBB0_253:
	v_readlane_b32 s86, v254, 22
	v_readlane_b32 s87, v254, 23
	v_readlane_b32 s0, v251, 53
	v_or_b32_e32 v62, s34, v104
	v_lshlrev_b64 v[60:61], 12, v[80:81]
	v_readlane_b32 s1, v251, 54
	v_lshlrev_b32_e32 v156, 1, v62
	v_cmp_gt_i32_e32 vcc, 64, v97
	s_waitcnt vmcnt(5)
	v_lshl_add_u64 v[0:1], s[0:1], 0, v[60:61]
	v_lshl_add_u64 v[0:1], v[0:1], 0, v[156:157]
	global_load_dwordx4 v[56:59], v[0:1], off
	global_load_dwordx4 v[16:19], v[0:1], off offset:128
	global_load_dwordx4 v[4:7], v[0:1], off offset:256
	s_nop 0
	global_load_dwordx4 v[0:3], v[0:1], off offset:384
	v_lshlrev_b32_e32 v236, 2, v62
	global_load_dwordx4 v[204:207], v236, s[86:87] offset:16
	global_load_dwordx4 v[208:211], v236, s[86:87]
	global_load_dwordx4 v[212:215], v236, s[86:87] offset:272
	global_load_dwordx4 v[216:219], v236, s[86:87] offset:256
	global_load_dwordx4 v[220:223], v236, s[86:87] offset:528
	global_load_dwordx4 v[224:227], v236, s[86:87] offset:512
	global_load_dwordx4 v[228:231], v236, s[86:87] offset:784
	global_load_dwordx4 v[232:235], v236, s[86:87] offset:768
	s_and_saveexec_b64 s[0:1], vcc
	s_cbranch_execz .LBB0_197
	s_waitcnt vmcnt(15)
	v_lshl_add_u32 v8, v95, 4, 16
	v_add_u32_e32 v8, 0x23c00, v8
	ds_write_b128 v8, v[136:139]
	ds_write_b128 v8, v[140:143] offset:64
	ds_write_b128 v8, v[148:151] offset:128
	ds_write_b128 v8, v[152:155] offset:192
	v_add_u32_e32 v9, 0x23c00, v99
	s_waitcnt lgkmcnt(0)
	ds_read_b32 v83, v9
	v_add_u32_e32 v8, 0x23800, v99
	ds_read_b32 v8, v8
	v_add_u32_e32 v9, 0x23b00, v99
	v_add_u32_e32 v10, 0x23900, v99
	ds_read_b32 v10, v10
	ds_read_b32 v9, v9
	s_waitcnt lgkmcnt(2)
	v_sub_f32_e32 v8, v100, v8
	v_mul_f32_e32 v8, 0x3fb8aa3b, v8
	v_exp_f32_e32 v8, v8
	s_waitcnt lgkmcnt(1)
	v_mul_f32_e32 v10, 0xbfb8aa3b, v10
	v_exp_f32_e32 v10, v10
	s_waitcnt lgkmcnt(0)
	v_fmac_f32_e32 v83, v9, v8
	v_max_f32_e64 v8, |v83|, v10
	v_div_scale_f32 v9, s[8:9], v8, v8, 1.0
	v_rcp_f32_e32 v10, v9
	v_div_scale_f32 v11, vcc, 1.0, v8, 1.0
	s_waitcnt vmcnt(14)
	v_fma_f32 v12, -v9, v10, 1.0
	v_fmac_f32_e32 v10, v12, v10
	v_mul_f32_e32 v12, v11, v10
	v_fma_f32 v13, -v9, v12, v11
	v_fmac_f32_e32 v12, v13, v10
	v_fma_f32 v9, -v9, v12, v11
	v_div_fmas_f32 v9, v9, v10, v12
	v_div_fixup_f32 v8, v9, v8, 1.0
	v_add_u32_e32 v9, 0x23a00, v99
	ds_write_b32 v9, v8
	s_branch .LBB0_197
